# P7: the 64 workgroups without a GEMM unit read x_prompt/x_sample (one dword per 64 B) during the K loop so the epilogue's residual reads hit the memory-side cache
# speedup vs baseline: 1.0134x; 1.0117x over previous
.LBB0_1245:
	s_barrier
	s_branch .LBB0_1246
.Lpf7:
	s_load_dwordx4 s[24:27], s[0:1], 0x0
	s_sub_i32 s18, s2, 0xc0
	s_lshr_b32 s19, s45, 6
	v_and_b32_e32 v0, 63, v170
	v_lshlrev_b32_e32 v0, 6, v0
	s_lshl_b32 s20, s18, 18
	s_lshl_b32 s21, s19, 15
	s_add_u32 s20, s20, s21
	s_lshl_b32 s22, s18, 19
	s_lshl_b32 s23, s19, 16
	s_add_u32 s22, s22, s23
	s_waitcnt lgkmcnt(0)
	s_add_u32 s24, s24, s20
	s_addc_u32 s25, s25, 0
	s_add_u32 s26, s26, s22
	s_addc_u32 s27, s27, 0
	global_load_dword v1, v0, s[24:25]
	s_add_u32 s24, s24, 0x1000
	s_addc_u32 s25, s25, 0
	global_load_dword v2, v0, s[24:25]
	s_add_u32 s24, s24, 0x1000
	s_addc_u32 s25, s25, 0
	global_load_dword v3, v0, s[24:25]
	s_add_u32 s24, s24, 0x1000
	s_addc_u32 s25, s25, 0
	global_load_dword v4, v0, s[24:25]
	s_waitcnt vmcnt(0)
	s_add_u32 s24, s24, 0x1000
	s_addc_u32 s25, s25, 0
	global_load_dword v1, v0, s[24:25]
	s_add_u32 s24, s24, 0x1000
	s_addc_u32 s25, s25, 0
	global_load_dword v2, v0, s[24:25]
	s_add_u32 s24, s24, 0x1000
	s_addc_u32 s25, s25, 0
	global_load_dword v3, v0, s[24:25]
	s_add_u32 s24, s24, 0x1000
	s_addc_u32 s25, s25, 0
	global_load_dword v4, v0, s[24:25]
	s_waitcnt vmcnt(0)
	global_load_dword v1, v0, s[26:27]
	s_add_u32 s26, s26, 0x1000
	s_addc_u32 s27, s27, 0
	global_load_dword v2, v0, s[26:27]
	s_add_u32 s26, s26, 0x1000
	s_addc_u32 s27, s27, 0
	global_load_dword v3, v0, s[26:27]
	s_add_u32 s26, s26, 0x1000
	s_addc_u32 s27, s27, 0
	global_load_dword v4, v0, s[26:27]
	s_waitcnt vmcnt(0)
	s_add_u32 s26, s26, 0x1000
	s_addc_u32 s27, s27, 0
	global_load_dword v1, v0, s[26:27]
	s_add_u32 s26, s26, 0x1000
	s_addc_u32 s27, s27, 0
	global_load_dword v2, v0, s[26:27]
	s_add_u32 s26, s26, 0x1000
	s_addc_u32 s27, s27, 0
	global_load_dword v3, v0, s[26:27]
	s_add_u32 s26, s26, 0x1000
	s_addc_u32 s27, s27, 0
	global_load_dword v4, v0, s[26:27]
	s_waitcnt vmcnt(0)
	s_add_u32 s26, s26, 0x1000
	s_addc_u32 s27, s27, 0
	global_load_dword v1, v0, s[26:27]
	s_add_u32 s26, s26, 0x1000
	s_addc_u32 s27, s27, 0
	global_load_dword v2, v0, s[26:27]
	s_add_u32 s26, s26, 0x1000
	s_addc_u32 s27, s27, 0
	global_load_dword v3, v0, s[26:27]
	s_add_u32 s26, s26, 0x1000
	s_addc_u32 s27, s27, 0
	global_load_dword v4, v0, s[26:27]
	s_waitcnt vmcnt(0)
	s_add_u32 s26, s26, 0x1000
	s_addc_u32 s27, s27, 0
	global_load_dword v1, v0, s[26:27]
	s_add_u32 s26, s26, 0x1000
	s_addc_u32 s27, s27, 0
	global_load_dword v2, v0, s[26:27]
	s_add_u32 s26, s26, 0x1000
	s_addc_u32 s27, s27, 0
	global_load_dword v3, v0, s[26:27]
	s_add_u32 s26, s26, 0x1000
	s_addc_u32 s27, s27, 0
	global_load_dword v4, v0, s[26:27]
	s_waitcnt vmcnt(0)
	s_branch .LBB0_1246
